# LayerNorm loops: waits for the modulation vectors no longer cover the row prefetch issued after them (iterations without a prefetch drain once instead)
# baseline (speedup 1.0000x reference)
.LBB0_1220:
	s_waitcnt vmcnt(7)
	v_pk_add_f32 v[68:69], v[68:69], 1.0 op_sel_hi:[1,0]
	s_add_i32 s3, s3, 1
	s_addk_i32 s10, 0x100
	v_mov_b64_e32 v[110:111], v[62:63]
	v_mov_b64_e32 v[106:107], v[58:59]
	v_mov_b64_e32 v[102:103], v[54:55]
	v_mov_b64_e32 v[90:91], v[50:51]
	v_pk_add_f32 v[70:71], v[70:71], 1.0 op_sel_hi:[1,0]
	v_pk_fma_f32 v[64:65], v[68:69], v[74:75], v[64:65]
	s_cmp_lg_u32 s11, s3
	v_mov_b64_e32 v[108:109], v[60:61]
	v_mov_b64_e32 v[104:105], v[56:57]
	v_mov_b64_e32 v[100:101], v[52:53]
	v_mov_b64_e32 v[88:89], v[48:49]
	v_pk_fma_f32 v[66:67], v[70:71], v[72:73], v[66:67]
	v_cvt_pk_bf16_f32 v64, v64, v65
	s_nop 0
	v_cvt_pk_bf16_f32 v65, v66, v67
	global_store_dwordx2 v[92:93], v[64:65], off offset:1536
	s_cbranch_scc0 .LBB0_1235
.LBB0_1221:
	s_cmp_lt_u32 s3, 8
	s_cselect_b32 s12, s10, s18
	s_add_i32 s92, s12, 0xffffc000
	s_lshr_b32 s9, s92, 2
	s_ashr_i32 s8, s12, 11
	s_add_i32 s9, s9, 8
	s_cmpk_lt_i32 s12, 0x4000
	s_cselect_b32 s8, s8, s9
	v_readlane_b32 s9, v255, 4
	s_add_i32 s8, s8, s9
	s_mul_hi_i32 s9, s8, 0x9000
	s_mul_i32 s8, s8, 0x9000
	s_add_u32 s8, s19, s8
	s_addc_u32 s9, s20, s9
	s_add_u32 s14, s8, 0x1000
	s_addc_u32 s15, s9, 0
	global_load_dwordx4 v[92:95], v144, s[8:9]
	global_load_dwordx4 v[80:83], v144, s[8:9] offset:1024
	global_load_dwordx4 v[96:99], v144, s[14:15]
	global_load_dwordx4 v[84:87], v159, s[14:15]
	global_load_dwordx4 v[72:75], v144, s[8:9] offset:2048
	global_load_dwordx4 v[64:67], v144, s[8:9] offset:3072
	global_load_dwordx4 v[76:79], v160, s[14:15]
	global_load_dwordx4 v[68:71], v161, s[14:15]
	s_waitcnt vmcnt(12)
	v_mov_b64_e32 v[50:51], v[46:47]
	v_mov_b64_e32 v[54:55], v[42:43]
	v_mov_b64_e32 v[58:59], v[34:35]
	s_add_i32 s8, s3, 2
	v_mov_b64_e32 v[62:63], v[38:39]
	v_mov_b64_e32 v[48:49], v[44:45]
	v_mov_b64_e32 v[52:53], v[40:41]
	v_mov_b64_e32 v[56:57], v[32:33]
	s_cmp_ge_u32 s8, s11
	v_mov_b64_e32 v[60:61], v[36:37]
	s_cbranch_scc1 .Lmy_lnA_noprefetch
	s_add_i32 s8, s10, 0x200
	s_cmp_lt_u32 s3, 6
	s_cselect_b32 s8, s8, s18
	s_ashr_i32 s9, s8, 31
	s_lshl_b64 s[8:9], s[8:9], 12
	v_lshl_add_u64 v[44:45], v[154:155], 0, s[8:9]
	global_load_dwordx4 v[36:39], v[44:45], off
	global_load_dwordx4 v[32:35], v[44:45], off offset:1024
	global_load_dwordx4 v[40:43], v[44:45], off offset:2048
	s_nop 0
	global_load_dwordx4 v[44:47], v[44:45], off offset:3072
	s_branch .LBB0_1223
.Lmy_lnA_noprefetch:
	s_waitcnt vmcnt(0)
.LBB0_1223:
	s_cmpk_gt_i32 s12, 0x3fff
	s_cselect_b64 s[14:15], -1, 0
	s_cmpk_lt_i32 s12, 0x4000
	s_cbranch_scc1 .LBB0_1225
	s_lshl_b64 s[8:9], s[92:93], 12
	s_add_u32 s8, s21, s8
	s_addc_u32 s9, s22, s9
	s_add_u32 s16, s8, 0x400000
	s_addc_u32 s17, s9, 0
	global_load_dwordx4 v[140:143], v144, s[16:17]
	global_load_dwordx4 v[136:139], v159, s[16:17]
	global_load_dwordx4 v[132:135], v160, s[16:17]
	global_load_dwordx4 v[128:131], v161, s[16:17]
	s_add_u32 s16, s8, 0x600000
	s_addc_u32 s17, s9, 0
	global_load_dwordx4 v[124:127], v144, s[16:17]
	global_load_dwordx4 v[120:123], v159, s[16:17]
	global_load_dwordx4 v[116:119], v160, s[16:17]
	global_load_dwordx4 v[112:115], v161, s[16:17]
	global_load_dwordx4 v[162:165], v144, s[8:9] offset:3072
	global_load_dwordx4 v[166:169], v144, s[8:9] offset:2048
	global_load_dwordx4 v[170:173], v144, s[8:9] offset:1024
	global_load_dwordx4 v[174:177], v144, s[8:9]
	s_add_u32 s8, s8, 0x200000
	s_addc_u32 s9, s9, 0
	s_waitcnt vmcnt(3)
	v_pk_add_f32 v[164:165], v[90:91], v[164:165]
	s_waitcnt vmcnt(2)
	v_pk_add_f32 v[168:169], v[102:103], v[168:169]
	s_waitcnt vmcnt(1)
	v_pk_add_f32 v[172:173], v[106:107], v[172:173]
	s_waitcnt vmcnt(0)
	v_pk_add_f32 v[176:177], v[110:111], v[176:177]
	v_pk_add_f32 v[174:175], v[108:109], v[174:175]
	v_pk_add_f32 v[170:171], v[104:105], v[170:171]
	v_pk_add_f32 v[166:167], v[100:101], v[166:167]
	v_pk_add_f32 v[162:163], v[88:89], v[162:163]
	global_load_dwordx4 v[88:91], v161, s[8:9]
	global_load_dwordx4 v[100:103], v160, s[8:9]
	global_load_dwordx4 v[104:107], v159, s[8:9]
	global_load_dwordx4 v[108:111], v144, s[8:9]
	s_waitcnt vmcnt(3)
	v_pk_add_f32 v[90:91], v[164:165], v[90:91]
	s_waitcnt vmcnt(2)
	v_pk_add_f32 v[102:103], v[168:169], v[102:103]
	s_waitcnt vmcnt(1)
	v_pk_add_f32 v[106:107], v[172:173], v[106:107]
	s_waitcnt vmcnt(0)
	v_pk_add_f32 v[110:111], v[176:177], v[110:111]
	v_pk_add_f32 v[108:109], v[174:175], v[108:109]
	v_pk_add_f32 v[104:105], v[170:171], v[104:105]
	v_pk_add_f32 v[100:101], v[166:167], v[100:101]
	v_pk_add_f32 v[88:89], v[162:163], v[88:89]
	v_pk_add_f32 v[110:111], v[142:143], v[110:111]
	v_pk_add_f32 v[108:109], v[140:141], v[108:109]
	v_pk_add_f32 v[106:107], v[138:139], v[106:107]
	v_pk_add_f32 v[104:105], v[136:137], v[104:105]
	v_pk_add_f32 v[102:103], v[134:135], v[102:103]
	v_pk_add_f32 v[100:101], v[132:133], v[100:101]
	v_pk_add_f32 v[90:91], v[130:131], v[90:91]
	v_pk_add_f32 v[88:89], v[128:129], v[88:89]
	v_pk_add_f32 v[110:111], v[126:127], v[110:111]
	v_pk_add_f32 v[108:109], v[124:125], v[108:109]
	v_pk_add_f32 v[106:107], v[122:123], v[106:107]
	v_pk_add_f32 v[104:105], v[120:121], v[104:105]
	v_pk_add_f32 v[102:103], v[118:119], v[102:103]
	v_pk_add_f32 v[100:101], v[116:117], v[100:101]
	v_pk_add_f32 v[90:91], v[114:115], v[90:91]
	v_pk_add_f32 v[88:89], v[112:113], v[88:89]

.LBB0_1229:
	s_waitcnt vmcnt(9)
	v_pk_add_f32 v[98:99], v[98:99], 1.0 op_sel_hi:[1,0]
	v_pk_add_f32 v[96:97], v[96:97], 1.0 op_sel_hi:[1,0]
	s_lshl_b64 s[12:13], s[12:13], 10
	v_pk_fma_f32 v[94:95], v[98:99], v[108:109], v[94:95]
	v_pk_fma_f32 v[92:93], v[96:97], v[112:113], v[92:93]
	v_mov_b32_e32 v114, v104
	v_mov_b32_e32 v115, v110
	v_mov_b32_e32 v107, v106
	v_cvt_pk_bf16_f32 v96, v92, v93
	v_cvt_pk_bf16_f32 v97, v94, v95
	v_lshl_add_u64 v[92:93], s[12:13], 1, v[156:157]
	v_mov_b32_e32 v94, v106
	v_mov_b32_e32 v95, v106
	v_mov_b32_e32 v104, v111
	global_store_dwordx2 v[92:93], v[96:97], off
	v_pk_mul_f32 v[96:97], v[104:105], v[94:95]
	v_pk_mul_f32 v[98:99], v[114:115], v[106:107]
	v_pk_fma_f32 v[96:97], v[6:7], v[96:97], v[14:15]
	s_and_b64 vcc, exec, s[8:9]
	v_pk_fma_f32 v[98:99], v[4:5], v[98:99], v[12:13]
	s_cbranch_vccnz .LBB0_1231
	v_pk_mul_f32 v[110:111], v[96:97], s[58:59] op_sel_hi:[1,0]
	v_pk_mul_f32 v[108:109], v[98:99], s[58:59] op_sel_hi:[1,0]
	global_store_dwordx4 v144, v[108:111], s[16:17] offset:1024
.LBB0_1231:
	s_waitcnt vmcnt(9)
	v_pk_add_f32 v[84:85], v[84:85], 1.0 op_sel_hi:[1,0]
	v_pk_add_f32 v[86:87], v[86:87], 1.0 op_sel_hi:[1,0]
	v_pk_fma_f32 v[80:81], v[84:85], v[98:99], v[80:81]
	v_pk_fma_f32 v[82:83], v[86:87], v[96:97], v[82:83]
	v_cvt_pk_bf16_f32 v80, v80, v81
	s_and_b64 vcc, exec, s[8:9]
	v_cvt_pk_bf16_f32 v81, v82, v83
	global_store_dwordx2 v[92:93], v[80:81], off offset:512
	v_pk_mul_f32 v[80:81], v[102:103], v[94:95]
	v_pk_mul_f32 v[82:83], v[100:101], v[106:107]
	v_pk_fma_f32 v[80:81], v[18:19], v[80:81], v[26:27]
	v_pk_fma_f32 v[82:83], v[16:17], v[82:83], v[24:25]
	s_cbranch_vccnz .LBB0_1233
	v_pk_mul_f32 v[86:87], v[80:81], s[58:59] op_sel_hi:[1,0]
	v_pk_mul_f32 v[84:85], v[82:83], s[58:59] op_sel_hi:[1,0]
	global_store_dwordx4 v144, v[84:87], s[16:17] offset:2048
.LBB0_1233:
	s_waitcnt vmcnt(7)
	v_pk_add_f32 v[76:77], v[76:77], 1.0 op_sel_hi:[1,0]
	v_pk_add_f32 v[78:79], v[78:79], 1.0 op_sel_hi:[1,0]
	v_pk_fma_f32 v[72:73], v[76:77], v[82:83], v[72:73]
	v_pk_fma_f32 v[74:75], v[78:79], v[80:81], v[74:75]
	v_cvt_pk_bf16_f32 v72, v72, v73
	s_and_b64 vcc, exec, s[8:9]
	v_cvt_pk_bf16_f32 v73, v74, v75
	global_store_dwordx2 v[92:93], v[72:73], off offset:1024
	v_mov_b32_e32 v72, v106
	v_mov_b32_e32 v73, v106
	v_pk_mul_f32 v[72:73], v[90:91], v[72:73]
	v_pk_mul_f32 v[74:75], v[88:89], v[106:107]
	v_pk_fma_f32 v[72:73], v[22:23], v[72:73], v[30:31]
	v_pk_fma_f32 v[74:75], v[20:21], v[74:75], v[28:29]
	s_cbranch_vccnz .LBB0_1220
	v_pk_mul_f32 v[78:79], v[72:73], s[58:59] op_sel_hi:[1,0]
	v_pk_mul_f32 v[76:77], v[74:75], s[58:59] op_sel_hi:[1,0]
	global_store_dwordx4 v144, v[76:79], s[16:17] offset:3072
	s_branch .LBB0_1220

.LBB0_1469:
	s_waitcnt vmcnt(7)
	v_pk_add_f32 v[68:69], v[68:69], 1.0 op_sel_hi:[1,0]
	s_add_i32 s3, s3, 1
	v_mov_b64_e32 v[102:103], v[62:63]
	v_mov_b64_e32 v[106:107], v[58:59]
	v_mov_b64_e32 v[110:111], v[54:55]
	v_mov_b64_e32 v[90:91], v[50:51]
	v_pk_add_f32 v[70:71], v[70:71], 1.0 op_sel_hi:[1,0]
	v_pk_fma_f32 v[64:65], v[68:69], v[74:75], v[64:65]
	s_cmp_eq_u32 s3, s13
	v_mov_b64_e32 v[100:101], v[60:61]
	v_mov_b64_e32 v[104:105], v[56:57]
	v_mov_b64_e32 v[108:109], v[52:53]
	v_mov_b64_e32 v[88:89], v[48:49]
	v_pk_fma_f32 v[66:67], v[70:71], v[72:73], v[66:67]
	v_cvt_pk_bf16_f32 v64, v64, v65
	s_nop 0
	v_cvt_pk_bf16_f32 v65, v66, v67
	global_store_dwordx2 v[92:93], v[64:65], off offset:1536
	s_cbranch_scc1 .LBB0_1489
.LBB0_1470:
	s_lshl_b32 s8, s3, 8
	s_add_i32 s8, s8, s12
	s_cmp_lt_u32 s3, 8
	s_cselect_b32 s14, s8, s20
	s_add_i32 s92, s14, 0xffffc000
	s_lshr_b32 s9, s92, 2
	s_ashr_i32 s8, s14, 11
	s_add_i32 s9, s9, 8
	s_cmpk_lt_i32 s14, 0x4000
	s_cselect_b32 s8, s8, s9
	v_readlane_b32 s9, v255, 4
	s_add_i32 s8, s8, s9
	s_mul_hi_i32 s9, s8, 0x9000
	s_mul_i32 s8, s8, 0x9000
	s_add_u32 s8, s21, s8
	s_addc_u32 s9, s22, s9
	s_add_u32 s16, s8, 0x1000
	s_addc_u32 s17, s9, 0
	global_load_dwordx4 v[92:95], v130, s[8:9]
	global_load_dwordx4 v[80:83], v130, s[8:9] offset:1024
	global_load_dwordx4 v[96:99], v130, s[16:17]
	global_load_dwordx4 v[84:87], v131, s[16:17]
	global_load_dwordx4 v[72:75], v130, s[8:9] offset:2048
	global_load_dwordx4 v[64:67], v130, s[8:9] offset:3072
	global_load_dwordx4 v[76:79], v132, s[16:17]
	global_load_dwordx4 v[68:71], v133, s[16:17]
	s_waitcnt vmcnt(12)
	v_mov_b64_e32 v[50:51], v[46:47]
	v_mov_b64_e32 v[54:55], v[42:43]
	v_mov_b64_e32 v[58:59], v[34:35]
	s_add_i32 s8, s3, 2
	v_mov_b64_e32 v[62:63], v[38:39]
	v_mov_b64_e32 v[48:49], v[44:45]
	v_mov_b64_e32 v[52:53], v[40:41]
	v_mov_b64_e32 v[56:57], v[32:33]
	s_cmp_ge_u32 s8, s13
	v_mov_b64_e32 v[60:61], v[36:37]
	s_cbranch_scc1 .Lmy_lnB_noprefetch
	s_lshl_b32 s8, s8, 8
	s_add_i32 s8, s8, s12
	s_cmp_lt_u32 s3, 6
	s_cselect_b32 s8, s8, s20
	s_ashr_i32 s9, s8, 31
	s_lshl_b64 s[8:9], s[8:9], 12
	v_lshl_add_u64 v[44:45], v[120:121], 0, s[8:9]
	global_load_dwordx4 v[36:39], v[44:45], off
	global_load_dwordx4 v[32:35], v[44:45], off offset:1024
	global_load_dwordx4 v[40:43], v[44:45], off offset:2048
	s_nop 0
	global_load_dwordx4 v[44:47], v[44:45], off offset:3072
	s_branch .LBB0_1472
.Lmy_lnB_noprefetch:
	s_waitcnt vmcnt(0)
.LBB0_1472:
	s_cmpk_gt_i32 s14, 0x3fff
	s_cselect_b64 s[16:17], -1, 0
	s_mov_b64 s[8:9], -1
	s_and_b64 vcc, exec, s[16:17]
	s_cbranch_vccnz .LBB0_1474
	s_mov_b64 s[8:9], 0

.LBB0_1483:
	s_waitcnt vmcnt(9)
	v_pk_add_f32 v[98:99], v[98:99], 1.0 op_sel_hi:[1,0]
	v_pk_add_f32 v[96:97], v[96:97], 1.0 op_sel_hi:[1,0]
	s_lshl_b64 s[14:15], s[14:15], 10
	v_pk_fma_f32 v[94:95], v[98:99], v[108:109], v[94:95]
	v_pk_fma_f32 v[92:93], v[96:97], v[110:111], v[92:93]
	v_mov_b32_e32 v101, v100
	v_cvt_pk_bf16_f32 v96, v92, v93
	v_cvt_pk_bf16_f32 v97, v94, v95
	v_lshl_add_u64 v[92:93], s[14:15], 1, v[122:123]
	v_mov_b32_e32 v94, v100
	v_mov_b32_e32 v95, v100
	global_store_dwordx2 v[92:93], v[96:97], off
	v_pk_mul_f32 v[96:97], v[106:107], v[94:95]
	v_pk_mul_f32 v[98:99], v[112:113], v[100:101]
	v_pk_fma_f32 v[96:97], v[6:7], v[96:97], v[14:15]
	s_and_b64 vcc, exec, s[8:9]
	v_pk_fma_f32 v[98:99], v[4:5], v[98:99], v[12:13]
	s_cbranch_vccnz .LBB0_1485
	v_pk_mul_f32 v[108:109], v[96:97], s[58:59] op_sel_hi:[1,0]
	v_pk_mul_f32 v[106:107], v[98:99], s[58:59] op_sel_hi:[1,0]
	global_store_dwordx4 v130, v[106:109], s[18:19] offset:1024
.LBB0_1485:
	s_waitcnt vmcnt(9)
	v_pk_add_f32 v[84:85], v[84:85], 1.0 op_sel_hi:[1,0]
	v_pk_add_f32 v[86:87], v[86:87], 1.0 op_sel_hi:[1,0]
	v_pk_fma_f32 v[80:81], v[84:85], v[98:99], v[80:81]
	v_pk_fma_f32 v[82:83], v[86:87], v[96:97], v[82:83]
	v_cvt_pk_bf16_f32 v80, v80, v81
	s_and_b64 vcc, exec, s[8:9]
	v_cvt_pk_bf16_f32 v81, v82, v83
	global_store_dwordx2 v[92:93], v[80:81], off offset:512
	v_pk_mul_f32 v[80:81], v[102:103], v[94:95]
	v_pk_mul_f32 v[82:83], v[104:105], v[100:101]
	v_pk_fma_f32 v[80:81], v[18:19], v[80:81], v[26:27]
	v_pk_fma_f32 v[82:83], v[16:17], v[82:83], v[24:25]
	s_cbranch_vccnz .LBB0_1487
	v_pk_mul_f32 v[86:87], v[80:81], s[58:59] op_sel_hi:[1,0]
	v_pk_mul_f32 v[84:85], v[82:83], s[58:59] op_sel_hi:[1,0]
	global_store_dwordx4 v130, v[84:87], s[18:19] offset:2048
.LBB0_1487:
	s_waitcnt vmcnt(7)
	v_pk_add_f32 v[76:77], v[76:77], 1.0 op_sel_hi:[1,0]
	v_pk_add_f32 v[78:79], v[78:79], 1.0 op_sel_hi:[1,0]
	v_pk_fma_f32 v[72:73], v[76:77], v[82:83], v[72:73]
	v_pk_fma_f32 v[74:75], v[78:79], v[80:81], v[74:75]
	v_cvt_pk_bf16_f32 v72, v72, v73
	s_and_b64 vcc, exec, s[8:9]
	v_cvt_pk_bf16_f32 v73, v74, v75
	global_store_dwordx2 v[92:93], v[72:73], off offset:1024
	v_mov_b32_e32 v72, v100
	v_mov_b32_e32 v73, v100
	v_pk_mul_f32 v[72:73], v[90:91], v[72:73]
	v_pk_mul_f32 v[74:75], v[88:89], v[100:101]
	v_pk_fma_f32 v[72:73], v[22:23], v[72:73], v[30:31]
	v_pk_fma_f32 v[74:75], v[20:21], v[74:75], v[28:29]
	s_cbranch_vccnz .LBB0_1469
	v_pk_mul_f32 v[78:79], v[72:73], s[58:59] op_sel_hi:[1,0]
	v_pk_mul_f32 v[76:77], v[74:75], s[58:59] op_sel_hi:[1,0]
	global_store_dwordx4 v130, v[76:79], s[18:19] offset:3072
	s_branch .LBB0_1469
